# GEMM unit loops: accumulator zeroing with 64 v_mov_b64 (inline 0) instead of 128 v_mov_b32 copies
# baseline (speedup 1.0000x reference)
; template <class Epi, class Sched, bool ALIGN_EPI = false, bool SP2 = false>
; __device__ __forceinline__ void gemm_phase(PG8_LAS unsigned char* lds, const Gemm g, const Sched& S, const Epi& E) {
;     ...
;         const bool has_next = S.next(ui + 1, nxt);
;         const char* nA = has_next ? (const char*)g.A + (size_t)nxt.pm * tstep : cA; const char* nB = has_next ? (const char*)g.Bt + (size_t)nxt.pn * tstep : cB;
;         for (int t = 0; t < nt; t += 2) {
;             const bool last = (t == nt - 2);
;             const char* a1 = cA + (size_t)(t + 1) * kstep;
;             const char* a2 = last ? nA : cA + (size_t)(t + 2) * kstep; const char* b2 = last ? nB : cB + (size_t)(t + 2) * kstep;
;             const char* a3 = a2 + kstep; const char* b3 = b2 + kstep;
;     ...
; #pragma unroll
;         for (int a = 0; a < 2; ++a)
; #pragma unroll
;             for (int b = 0; b < 2; ++b)
; #pragma unroll
;                 for (int m = 0; m < 4; ++m)
; #pragma unroll
;                     for (int n = 0; n < 2; ++n) acc[a][b][m][n] = (f32x4){0.f, 0.f, 0.f, 0.f};
;         cur = nxt; cA = nA; cB = nB; ++ui;
.LBB0_96:
	s_ashr_i32 s17, s16, 31
	s_lshl_b64 s[18:19], s[16:17], 19
	s_add_u32 s18, s31, s18
	s_addc_u32 s19, s34, s19
	s_and_b64 s[20:21], s[4:5], exec
	s_cselect_b32 s17, s19, s23
	s_cselect_b32 s44, s18, s22
	s_ashr_i32 s15, s14, 31
	s_lshl_b64 s[20:21], s[14:15], 19
	s_add_u32 s20, s35, s20
	s_addc_u32 s21, s64, s21
	s_and_b64 s[26:27], s[4:5], exec
	s_cselect_b32 s15, s21, s25
	s_cselect_b32 s45, s20, s24
	s_add_u32 s22, s22, 0x40080
	s_addc_u32 s23, s23, 0
	s_add_u32 s46, s24, 0x100
	v_mov_b64_e32 v[8:9], 0
	s_addc_u32 s47, s25, 0
	s_mov_b32 vcc_lo, -2
	v_mov_b64_e32 v[10:11], 0
	v_mov_b64_e32 v[16:17], 0
	v_mov_b64_e32 v[18:19], 0
	v_mov_b64_e32 v[24:25], 0
	v_mov_b64_e32 v[26:27], 0
	v_mov_b64_e32 v[32:33], 0
	v_mov_b64_e32 v[34:35], 0
	v_mov_b64_e32 v[40:41], 0
	v_mov_b64_e32 v[42:43], 0
	v_mov_b64_e32 v[48:49], 0
	v_mov_b64_e32 v[50:51], 0
	v_mov_b64_e32 v[56:57], 0
	v_mov_b64_e32 v[58:59], 0
	v_mov_b64_e32 v[64:65], 0
	v_mov_b64_e32 v[66:67], 0
	v_mov_b64_e32 v[12:13], 0
	v_mov_b64_e32 v[14:15], 0
	v_mov_b64_e32 v[20:21], 0
	v_mov_b64_e32 v[22:23], 0
	v_mov_b64_e32 v[28:29], 0
	v_mov_b64_e32 v[30:31], 0
	v_mov_b64_e32 v[36:37], 0
	v_mov_b64_e32 v[38:39], 0
	v_mov_b64_e32 v[44:45], 0
	v_mov_b64_e32 v[46:47], 0
	v_mov_b64_e32 v[52:53], 0
	v_mov_b64_e32 v[54:55], 0
	v_mov_b64_e32 v[60:61], 0
	v_mov_b64_e32 v[62:63], 0
	v_mov_b64_e32 v[68:69], 0
	v_mov_b64_e32 v[70:71], 0
	v_mov_b64_e32 v[72:73], 0
	v_mov_b64_e32 v[74:75], 0
	v_mov_b64_e32 v[80:81], 0
	v_mov_b64_e32 v[82:83], 0
	v_mov_b64_e32 v[88:89], 0
	v_mov_b64_e32 v[90:91], 0
	v_mov_b64_e32 v[96:97], 0
	v_mov_b64_e32 v[98:99], 0
	v_mov_b64_e32 v[104:105], 0
	v_mov_b64_e32 v[106:107], 0
	v_mov_b64_e32 v[112:113], 0
	v_mov_b64_e32 v[114:115], 0
	v_mov_b64_e32 v[120:121], 0
	v_mov_b64_e32 v[122:123], 0
	v_mov_b64_e32 v[128:129], 0
	v_mov_b64_e32 v[130:131], 0
	v_mov_b64_e32 v[76:77], 0
	v_mov_b64_e32 v[78:79], 0
	v_mov_b64_e32 v[84:85], 0
	v_mov_b64_e32 v[86:87], 0
	v_mov_b64_e32 v[92:93], 0
	v_mov_b64_e32 v[94:95], 0
	v_mov_b64_e32 v[100:101], 0
	v_mov_b64_e32 v[102:103], 0
	v_mov_b64_e32 v[108:109], 0
	v_mov_b64_e32 v[110:111], 0
	v_mov_b64_e32 v[116:117], 0
	v_mov_b64_e32 v[118:119], 0
	v_mov_b64_e32 v[124:125], 0
	v_mov_b64_e32 v[126:127], 0
	v_mov_b64_e32 v[132:133], 0
	v_mov_b64_e32 v[134:135], 0

; template <class Epi, class Sched, bool ALIGN_EPI = false, bool SP2 = false>
; __device__ __forceinline__ void gemm_phase(PG8_LAS unsigned char* lds, const Gemm g, const Sched& S, const Epi& E) {
;     ...
; #pragma unroll
;         for (int a = 0; a < 2; ++a)
; #pragma unroll
;             for (int b = 0; b < 2; ++b)
; #pragma unroll
;                 for (int m = 0; m < 4; ++m)
; #pragma unroll
;                     for (int n = 0; n < 2; ++n) acc[a][b][m][n] = (f32x4){0.f, 0.f, 0.f, 0.f};
;         cur = nxt; cA = nA; cB = nB; ++ui;
.LBB0_176:
	s_add_u32 vcc_lo, s24, 0x100
	v_mov_b64_e32 v[0:1], 0
	s_addc_u32 vcc_hi, s25, 0
	s_mov_b32 s68, -2
	v_mov_b64_e32 v[2:3], 0
	v_mov_b64_e32 v[4:5], 0
	v_mov_b64_e32 v[6:7], 0
	v_mov_b64_e32 v[16:17], 0
	v_mov_b64_e32 v[18:19], 0
	v_mov_b64_e32 v[20:21], 0
	v_mov_b64_e32 v[22:23], 0
	v_mov_b64_e32 v[32:33], 0
	v_mov_b64_e32 v[34:35], 0
	v_mov_b64_e32 v[36:37], 0
	v_mov_b64_e32 v[38:39], 0
	v_mov_b64_e32 v[48:49], 0
	v_mov_b64_e32 v[50:51], 0
	v_mov_b64_e32 v[52:53], 0
	v_mov_b64_e32 v[54:55], 0
	v_mov_b64_e32 v[8:9], 0
	v_mov_b64_e32 v[10:11], 0
	v_mov_b64_e32 v[12:13], 0
	v_mov_b64_e32 v[14:15], 0
	v_mov_b64_e32 v[24:25], 0
	v_mov_b64_e32 v[26:27], 0
	v_mov_b64_e32 v[28:29], 0
	v_mov_b64_e32 v[30:31], 0
	v_mov_b64_e32 v[40:41], 0
	v_mov_b64_e32 v[42:43], 0
	v_mov_b64_e32 v[44:45], 0
	v_mov_b64_e32 v[46:47], 0
	v_mov_b64_e32 v[56:57], 0
	v_mov_b64_e32 v[58:59], 0
	v_mov_b64_e32 v[60:61], 0
	v_mov_b64_e32 v[62:63], 0
	v_mov_b64_e32 v[64:65], 0
	v_mov_b64_e32 v[66:67], 0
	v_mov_b64_e32 v[68:69], 0
	v_mov_b64_e32 v[70:71], 0
	v_mov_b64_e32 v[80:81], 0
	v_mov_b64_e32 v[82:83], 0
	v_mov_b64_e32 v[84:85], 0
	v_mov_b64_e32 v[86:87], 0
	v_mov_b64_e32 v[96:97], 0
	v_mov_b64_e32 v[98:99], 0
	v_mov_b64_e32 v[100:101], 0
	v_mov_b64_e32 v[102:103], 0
	v_mov_b64_e32 v[112:113], 0
	v_mov_b64_e32 v[114:115], 0
	v_mov_b64_e32 v[116:117], 0
	v_mov_b64_e32 v[118:119], 0
	v_mov_b64_e32 v[72:73], 0
	v_mov_b64_e32 v[74:75], 0
	v_mov_b64_e32 v[76:77], 0
	v_mov_b64_e32 v[78:79], 0
	v_mov_b64_e32 v[88:89], 0
	v_mov_b64_e32 v[90:91], 0
	v_mov_b64_e32 v[92:93], 0
	v_mov_b64_e32 v[94:95], 0
	v_mov_b64_e32 v[104:105], 0
	v_mov_b64_e32 v[106:107], 0
	v_mov_b64_e32 v[108:109], 0
	v_mov_b64_e32 v[110:111], 0
	v_mov_b64_e32 v[120:121], 0
	v_mov_b64_e32 v[122:123], 0
	v_mov_b64_e32 v[124:125], 0
	v_mov_b64_e32 v[126:127], 0

; template <class Epi, class Sched, bool ALIGN_EPI = false, bool SP2 = false>
; __device__ __forceinline__ void gemm_phase(PG8_LAS unsigned char* lds, const Gemm g, const Sched& S, const Epi& E) {
;     ...
;         const bool has_next = S.next(ui + 1, nxt);
;         const char* nA = has_next ? (const char*)g.A + (size_t)nxt.pm * tstep : cA; const char* nB = has_next ? (const char*)g.Bt + (size_t)nxt.pn * tstep : cB;
;         for (int t = 0; t < nt; t += 2) {
;             const bool last = (t == nt - 2);
;             const char* a1 = cA + (size_t)(t + 1) * kstep;
;             const char* a2 = last ? nA : cA + (size_t)(t + 2) * kstep; const char* b2 = last ? nB : cB + (size_t)(t + 2) * kstep;
;             const char* a3 = a2 + kstep; const char* b3 = b2 + kstep;
;     ...
; #pragma unroll
;         for (int a = 0; a < 2; ++a)
; #pragma unroll
;             for (int b = 0; b < 2; ++b)
; #pragma unroll
;                 for (int m = 0; m < 4; ++m)
; #pragma unroll
;                     for (int n = 0; n < 2; ++n) acc[a][b][m][n] = (f32x4){0.f, 0.f, 0.f, 0.f};
;         cur = nxt; cA = nA; cB = nB; ++ui;
.LBB0_269:
	s_ashr_i32 s19, s18, 31
	s_lshl_b64 s[20:21], s[18:19], 19
	s_add_u32 s20, s27, s20
	s_addc_u32 s21, s28, s21
	s_and_b64 s[22:23], s[4:5], exec
	s_cselect_b32 s19, s21, s7
	s_cselect_b32 s47, s20, s6
	s_ashr_i32 s17, s16, 31
	s_lshl_b64 s[22:23], s[16:17], 19
	s_add_u32 s22, s29, s22
	s_addc_u32 s23, s31, s23
	s_and_b64 s[24:25], s[4:5], exec
	s_cselect_b32 s17, s23, s9
	s_cselect_b32 s64, s22, s8
	s_add_u32 s6, s6, 0x40080
	s_addc_u32 s7, s7, 0
	s_add_u32 s65, s8, 0x100
	v_mov_b64_e32 v[0:1], 0
	s_addc_u32 s76, s9, 0
	s_mov_b32 s86, -2
	v_mov_b64_e32 v[2:3], 0
	v_mov_b64_e32 v[4:5], 0
	v_mov_b64_e32 v[6:7], 0
	v_mov_b64_e32 v[16:17], 0
	v_mov_b64_e32 v[18:19], 0
	v_mov_b64_e32 v[20:21], 0
	v_mov_b64_e32 v[22:23], 0
	v_mov_b64_e32 v[32:33], 0
	v_mov_b64_e32 v[34:35], 0
	v_mov_b64_e32 v[36:37], 0
	v_mov_b64_e32 v[38:39], 0
	v_mov_b64_e32 v[48:49], 0
	v_mov_b64_e32 v[50:51], 0
	v_mov_b64_e32 v[52:53], 0
	v_mov_b64_e32 v[54:55], 0
	v_mov_b64_e32 v[8:9], 0
	v_mov_b64_e32 v[10:11], 0
	v_mov_b64_e32 v[12:13], 0
	v_mov_b64_e32 v[14:15], 0
	v_mov_b64_e32 v[24:25], 0
	v_mov_b64_e32 v[26:27], 0
	v_mov_b64_e32 v[28:29], 0
	v_mov_b64_e32 v[30:31], 0
	v_mov_b64_e32 v[40:41], 0
	v_mov_b64_e32 v[42:43], 0
	v_mov_b64_e32 v[44:45], 0
	v_mov_b64_e32 v[46:47], 0
	v_mov_b64_e32 v[56:57], 0
	v_mov_b64_e32 v[58:59], 0
	v_mov_b64_e32 v[60:61], 0
	v_mov_b64_e32 v[62:63], 0
	v_mov_b64_e32 v[64:65], 0
	v_mov_b64_e32 v[66:67], 0
	v_mov_b64_e32 v[68:69], 0
	v_mov_b64_e32 v[70:71], 0
	v_mov_b64_e32 v[80:81], 0
	v_mov_b64_e32 v[82:83], 0
	v_mov_b64_e32 v[84:85], 0
	v_mov_b64_e32 v[86:87], 0
	v_mov_b64_e32 v[96:97], 0
	v_mov_b64_e32 v[98:99], 0
	v_mov_b64_e32 v[100:101], 0
	v_mov_b64_e32 v[102:103], 0
	v_mov_b64_e32 v[112:113], 0
	v_mov_b64_e32 v[114:115], 0
	v_mov_b64_e32 v[116:117], 0
	v_mov_b64_e32 v[118:119], 0
	v_mov_b64_e32 v[72:73], 0
	v_mov_b64_e32 v[74:75], 0
	v_mov_b64_e32 v[76:77], 0
	v_mov_b64_e32 v[78:79], 0
	v_mov_b64_e32 v[88:89], 0
	v_mov_b64_e32 v[90:91], 0
	v_mov_b64_e32 v[92:93], 0
	v_mov_b64_e32 v[94:95], 0
	v_mov_b64_e32 v[104:105], 0
	v_mov_b64_e32 v[106:107], 0
	v_mov_b64_e32 v[108:109], 0
	v_mov_b64_e32 v[110:111], 0
	v_mov_b64_e32 v[120:121], 0
	v_mov_b64_e32 v[122:123], 0
	v_mov_b64_e32 v[124:125], 0
	v_mov_b64_e32 v[126:127], 0

; template <class Epi, class Sched, bool ALIGN_EPI = false, bool SP2 = false>
; __device__ __forceinline__ void gemm_phase(PG8_LAS unsigned char* lds, const Gemm g, const Sched& S, const Epi& E) {
;     ...
;         const bool has_next = S.next(ui + 1, nxt);
;         const char* nA = has_next ? (const char*)g.A + (size_t)nxt.pm * tstep : cA; const char* nB = has_next ? (const char*)g.Bt + (size_t)nxt.pn * tstep : cB;
;         for (int t = 0; t < nt; t += 2) {
;             const bool last = (t == nt - 2);
;             const char* a1 = cA + (size_t)(t + 1) * kstep;
;             const char* a2 = last ? nA : cA + (size_t)(t + 2) * kstep; const char* b2 = last ? nB : cB + (size_t)(t + 2) * kstep;
;             const char* a3 = a2 + kstep; const char* b3 = b2 + kstep;
;     ...
; #pragma unroll
;         for (int a = 0; a < 2; ++a)
; #pragma unroll
;             for (int b = 0; b < 2; ++b)
; #pragma unroll
;                 for (int m = 0; m < 4; ++m)
; #pragma unroll
;                     for (int n = 0; n < 2; ++n) acc[a][b][m][n] = (f32x4){0.f, 0.f, 0.f, 0.f};
;         cur = nxt; cA = nA; cB = nB; ++ui;
.LBB0_506:
	s_ashr_i32 s21, s20, 31
	s_lshl_b64 s[22:23], s[20:21], 19
	s_add_u32 s22, s0, s22
	s_addc_u32 s23, s34, s23
	s_and_b64 s[24:25], s[6:7], exec
	s_cselect_b32 s21, s23, s27
	s_cselect_b32 s86, s22, s26
	s_ashr_i32 s19, s18, 31
	s_lshl_b64 s[24:25], s[18:19], 19
	s_add_u32 s24, s1, s24
	s_addc_u32 s25, s35, s25
	s_and_b64 s[30:31], s[6:7], exec
	s_cselect_b32 s19, s25, s29
	s_cselect_b32 s87, s24, s28
	s_add_u32 s26, s26, 0x40080
	s_addc_u32 s27, s27, 0
	s_add_u32 vcc_lo, s28, 0x100
	v_mov_b64_e32 v[0:1], 0
	s_addc_u32 vcc_hi, s29, 0
	s_mov_b32 s68, -2
	v_mov_b64_e32 v[2:3], 0
	v_mov_b64_e32 v[4:5], 0
	v_mov_b64_e32 v[6:7], 0
	v_mov_b64_e32 v[16:17], 0
	v_mov_b64_e32 v[18:19], 0
	v_mov_b64_e32 v[20:21], 0
	v_mov_b64_e32 v[22:23], 0
	v_mov_b64_e32 v[32:33], 0
	v_mov_b64_e32 v[34:35], 0
	v_mov_b64_e32 v[36:37], 0
	v_mov_b64_e32 v[38:39], 0
	v_mov_b64_e32 v[48:49], 0
	v_mov_b64_e32 v[50:51], 0
	v_mov_b64_e32 v[52:53], 0
	v_mov_b64_e32 v[54:55], 0
	v_mov_b64_e32 v[8:9], 0
	v_mov_b64_e32 v[10:11], 0
	v_mov_b64_e32 v[12:13], 0
	v_mov_b64_e32 v[14:15], 0
	v_mov_b64_e32 v[24:25], 0
	v_mov_b64_e32 v[26:27], 0
	v_mov_b64_e32 v[28:29], 0
	v_mov_b64_e32 v[30:31], 0
	v_mov_b64_e32 v[40:41], 0
	v_mov_b64_e32 v[42:43], 0
	v_mov_b64_e32 v[44:45], 0
	v_mov_b64_e32 v[46:47], 0
	v_mov_b64_e32 v[56:57], 0
	v_mov_b64_e32 v[58:59], 0
	v_mov_b64_e32 v[60:61], 0
	v_mov_b64_e32 v[62:63], 0
	v_mov_b64_e32 v[64:65], 0
	v_mov_b64_e32 v[66:67], 0
	v_mov_b64_e32 v[68:69], 0
	v_mov_b64_e32 v[70:71], 0
	v_mov_b64_e32 v[80:81], 0
	v_mov_b64_e32 v[82:83], 0
	v_mov_b64_e32 v[84:85], 0
	v_mov_b64_e32 v[86:87], 0
	v_mov_b64_e32 v[96:97], 0
	v_mov_b64_e32 v[98:99], 0
	v_mov_b64_e32 v[100:101], 0
	v_mov_b64_e32 v[102:103], 0
	v_mov_b64_e32 v[112:113], 0
	v_mov_b64_e32 v[114:115], 0
	v_mov_b64_e32 v[116:117], 0
	v_mov_b64_e32 v[118:119], 0
	v_mov_b64_e32 v[72:73], 0
	v_mov_b64_e32 v[74:75], 0
	v_mov_b64_e32 v[76:77], 0
	v_mov_b64_e32 v[78:79], 0
	v_mov_b64_e32 v[88:89], 0
	v_mov_b64_e32 v[90:91], 0
	v_mov_b64_e32 v[92:93], 0
	v_mov_b64_e32 v[94:95], 0
	v_mov_b64_e32 v[104:105], 0
	v_mov_b64_e32 v[106:107], 0
	v_mov_b64_e32 v[108:109], 0
	v_mov_b64_e32 v[110:111], 0
	v_mov_b64_e32 v[120:121], 0
	v_mov_b64_e32 v[122:123], 0
	v_mov_b64_e32 v[124:125], 0
	v_mov_b64_e32 v[126:127], 0
